# strategy 7.11 back-edge rotation: attention-A loop back edge, loop bookkeeping and pending-rescale checks moved in front of the step barriers so the post-barrier head falls through into the first MFMA
# speedup vs baseline: 1.0036x; 1.0036x over previous
; __device__ __forceinline__ void attn_unit_a(FLAS unsigned char* lds, const Unit u) {
;     ...
;         if (pend) {
; #pragma unroll
;             for (int d = 0; d < NDB; ++d) o[d] = o[d] * fpend;
;             pend = false; }
;     ...
;         __syncthreads();
.LBB0_433:
.LBB0_434:
	v_pk_mul_f32 v[62:63], v[62:63], v[226:227] op_sel_hi:[1,0]
	v_pk_mul_f32 v[60:61], v[60:61], v[226:227] op_sel_hi:[1,0]
	v_pk_mul_f32 v[58:59], v[58:59], v[226:227] op_sel_hi:[1,0]
	v_pk_mul_f32 v[56:57], v[56:57], v[226:227] op_sel_hi:[1,0]
	v_pk_mul_f32 v[54:55], v[54:55], v[226:227] op_sel_hi:[1,0]
	v_pk_mul_f32 v[52:53], v[52:53], v[226:227] op_sel_hi:[1,0]
	v_pk_mul_f32 v[50:51], v[50:51], v[226:227] op_sel_hi:[1,0]
	v_pk_mul_f32 v[48:49], v[48:49], v[226:227] op_sel_hi:[1,0]
	v_pk_mul_f32 v[46:47], v[46:47], v[226:227] op_sel_hi:[1,0]
	v_pk_mul_f32 v[44:45], v[44:45], v[226:227] op_sel_hi:[1,0]
	v_pk_mul_f32 v[42:43], v[42:43], v[226:227] op_sel_hi:[1,0]
	v_pk_mul_f32 v[40:41], v[40:41], v[226:227] op_sel_hi:[1,0]
	v_pk_mul_f32 v[38:39], v[38:39], v[226:227] op_sel_hi:[1,0]
	v_pk_mul_f32 v[36:37], v[36:37], v[226:227] op_sel_hi:[1,0]
	v_pk_mul_f32 v[34:35], v[34:35], v[226:227] op_sel_hi:[1,0]
	v_pk_mul_f32 v[32:33], v[32:33], v[226:227] op_sel_hi:[1,0]
	v_pk_mul_f32 v[30:31], v[30:31], v[226:227] op_sel_hi:[1,0]
	v_pk_mul_f32 v[28:29], v[28:29], v[226:227] op_sel_hi:[1,0]
	v_pk_mul_f32 v[26:27], v[26:27], v[226:227] op_sel_hi:[1,0]
	v_pk_mul_f32 v[24:25], v[24:25], v[226:227] op_sel_hi:[1,0]
	v_pk_mul_f32 v[22:23], v[22:23], v[226:227] op_sel_hi:[1,0]
	v_pk_mul_f32 v[20:21], v[20:21], v[226:227] op_sel_hi:[1,0]
	v_pk_mul_f32 v[18:19], v[18:19], v[226:227] op_sel_hi:[1,0]
	v_pk_mul_f32 v[16:17], v[16:17], v[226:227] op_sel_hi:[1,0]
	v_pk_mul_f32 v[14:15], v[14:15], v[226:227] op_sel_hi:[1,0]
	v_pk_mul_f32 v[12:13], v[12:13], v[226:227] op_sel_hi:[1,0]
	v_pk_mul_f32 v[10:11], v[10:11], v[226:227] op_sel_hi:[1,0]
	v_pk_mul_f32 v[8:9], v[8:9], v[226:227] op_sel_hi:[1,0]
	v_pk_mul_f32 v[6:7], v[6:7], v[226:227] op_sel_hi:[1,0]
	v_pk_mul_f32 v[4:5], v[4:5], v[226:227] op_sel_hi:[1,0]
	v_pk_mul_f32 v[2:3], v[2:3], v[226:227] op_sel_hi:[1,0]
	v_pk_mul_f32 v[0:1], v[0:1], v[226:227] op_sel_hi:[1,0]
.Ltop_bar:
	s_barrier

; __device__ __forceinline__ void attn_unit_a(FLAS unsigned char* lds, const Unit u) {
;     ...
;         if (pend) {
; #pragma unroll
;             for (int d = 0; d < NDB; ++d) o[d] = o[d] * fpend;
;             pend = false; }
;     ...
;         __syncthreads();
.LBB0_456:
	s_and_b64 vcc, exec, s[20:21]
	s_waitcnt lgkmcnt(0)
	s_cbranch_vccnz .Lpend_e

; #define FLAS __attribute__((address_space(3)))
; __device__ __forceinline__ void attn_unit_a(FLAS unsigned char* lds, const Unit u) {
;     ...
;         lsum += ps; cbC = cbN;
;         if (i + 2 < NT) { *(FLAS u32x4*)(lds + LA_K + (i & 1) * KBUF + kdst) = kreg;
; #pragma unroll
;             for (int j = 0; j < 2; ++j) { *(FLAS u32x2*)(lds + LA_V + ((i + 2) & 3) * VBUF + vdst + j * 64 * VPITCH) = (u32x2){vreg[j].x, vreg[j].y}; *(FLAS u32x2*)(lds + LA_V + ((i + 2) & 3) * VBUF + vdst + j * 64 * VPITCH + 16) = (u32x2){vreg[j].z, vreg[j].w}; } }
;         __syncthreads();
;     };
;     for (int i = 0; i < NT; i += 2) { step(i, pa0, pa1, pb0, pb1, pwa, pwb); if (i + 1 < NT) step(i + 1, pb0, pb1, pa0, pa1, pwb, pwa); }
;     if (pend) {
; #pragma unroll
;         for (int d = 0; d < NDB; ++d) o[d] = o[d] * fpend; }
;     if (NT & 1) { FA_PVP((NT - 1) & 3, pwb); } else { FA_PVP((NT - 1) & 3, pwa); }
.LBB0_476:
	s_add_u32 s52, s52, 0x100
	s_addc_u32 s53, s53, 0
	v_cvt_pk_bf16_f32 v206, v68, v69
	v_cvt_pk_bf16_f32 v207, v70, v71
	s_addk_i32 s48, 0x80
	s_addk_i32 s49, 0x200
	s_add_u32 s50, s50, 0x60000
	s_addc_u32 s51, s51, 0
	s_mov_b64 s[24:25], 0
	s_and_b64 vcc, exec, s[4:5]
	v_cvt_pk_bf16_f32 v204, v64, v65
	v_cvt_pk_bf16_f32 v205, v66, v67
	s_waitcnt lgkmcnt(0)
	s_cbranch_vccnz .Lexit_a
	s_mov_b32 s19, s34
	s_and_b64 vcc, exec, s[0:1]
	s_cbranch_vccnz .LBB0_434
	s_branch .Ltop_bar
.Lexit_a:
	s_barrier
	v_readlane_b32 s50, v255, 30
	v_readlane_b32 s51, v255, 31
	v_readlane_b32 s52, v255, 32
	v_readlane_b32 s53, v255, 33
	s_setprio 0
	s_andn2_b64 vcc, exec, s[0:1]
	s_cbranch_vccnz .LBB0_479
	v_pk_mul_f32 v[62:63], v[62:63], v[226:227] op_sel_hi:[1,0]
	v_pk_mul_f32 v[60:61], v[60:61], v[226:227] op_sel_hi:[1,0]
	v_pk_mul_f32 v[58:59], v[58:59], v[226:227] op_sel_hi:[1,0]
	v_pk_mul_f32 v[56:57], v[56:57], v[226:227] op_sel_hi:[1,0]
	v_pk_mul_f32 v[54:55], v[54:55], v[226:227] op_sel_hi:[1,0]
	v_pk_mul_f32 v[52:53], v[52:53], v[226:227] op_sel_hi:[1,0]
	v_pk_mul_f32 v[50:51], v[50:51], v[226:227] op_sel_hi:[1,0]
	v_pk_mul_f32 v[48:49], v[48:49], v[226:227] op_sel_hi:[1,0]
	v_pk_mul_f32 v[46:47], v[46:47], v[226:227] op_sel_hi:[1,0]
	v_pk_mul_f32 v[44:45], v[44:45], v[226:227] op_sel_hi:[1,0]
	v_pk_mul_f32 v[42:43], v[42:43], v[226:227] op_sel_hi:[1,0]
	v_pk_mul_f32 v[40:41], v[40:41], v[226:227] op_sel_hi:[1,0]
	v_pk_mul_f32 v[38:39], v[38:39], v[226:227] op_sel_hi:[1,0]
	v_pk_mul_f32 v[36:37], v[36:37], v[226:227] op_sel_hi:[1,0]
	v_pk_mul_f32 v[34:35], v[34:35], v[226:227] op_sel_hi:[1,0]
	v_pk_mul_f32 v[32:33], v[32:33], v[226:227] op_sel_hi:[1,0]
	v_pk_mul_f32 v[30:31], v[30:31], v[226:227] op_sel_hi:[1,0]
	v_pk_mul_f32 v[28:29], v[28:29], v[226:227] op_sel_hi:[1,0]
	v_pk_mul_f32 v[26:27], v[26:27], v[226:227] op_sel_hi:[1,0]
	v_pk_mul_f32 v[24:25], v[24:25], v[226:227] op_sel_hi:[1,0]
	v_pk_mul_f32 v[22:23], v[22:23], v[226:227] op_sel_hi:[1,0]
	v_pk_mul_f32 v[20:21], v[20:21], v[226:227] op_sel_hi:[1,0]
	v_pk_mul_f32 v[18:19], v[18:19], v[226:227] op_sel_hi:[1,0]
	v_pk_mul_f32 v[16:17], v[16:17], v[226:227] op_sel_hi:[1,0]
	v_pk_mul_f32 v[14:15], v[14:15], v[226:227] op_sel_hi:[1,0]
	v_pk_mul_f32 v[12:13], v[12:13], v[226:227] op_sel_hi:[1,0]
	v_pk_mul_f32 v[10:11], v[10:11], v[226:227] op_sel_hi:[1,0]
	v_pk_mul_f32 v[8:9], v[8:9], v[226:227] op_sel_hi:[1,0]
	v_pk_mul_f32 v[6:7], v[6:7], v[226:227] op_sel_hi:[1,0]
	v_pk_mul_f32 v[4:5], v[4:5], v[226:227] op_sel_hi:[1,0]
	v_pk_mul_f32 v[2:3], v[2:3], v[226:227] op_sel_hi:[1,0]
	v_pk_mul_f32 v[0:1], v[0:1], v[226:227] op_sel_hi:[1,0]
